# combo_earlyzero
# speedup vs baseline: 1.0129x; 1.0026x over previous
; #define STAGE(P, BASE, br, kt) do { const char* _gb = (const char*)(BASE) + ((size_t)(br) * K + (size_t)(kt) * BK) * 2; \
;     __builtin_amdgcn_global_load_lds((const unsigned*)(_gb + loff0), (unsigned*)((char*)(P) + tid * 16), 16, 0, 0); \
;     __builtin_amdgcn_global_load_lds((const unsigned*)(_gb + (size_t)K * 128 + loff0), (unsigned*)((char*)(P) + tid * 16 + 8192), 16, 0, 0); } while (0)
; #define WAIT_V(n) asm volatile("s_waitcnt vmcnt(" #n ")" ::: "memory")
; #define BAR __builtin_amdgcn_s_barrier()
; template <int EPI> ...
;     ...
;   f32x4 acc[2][2][4][2] = {};
;     ...
;   STAGE(SB(0, 0), Bt, bcol, 0); STAGE(SA(0, 0), A, brow, 0);
;   STAGE(SB(0, 1), Bt, bcol + HALF, 0); STAGE(SA(0, 1), A, brow + HALF, 0);
;   if (wr == 1) BAR;
;   WAIT_V(4); BAR;
;   STAGE(SB(1, 0), Bt, bcol, 1); STAGE(SA(1, 0), A, brow, 1); STAGE(SB(1, 1), Bt, bcol + HALF, 1);
;   WAIT_V(6); BAR;
.LBB0_273:
	s_mov_b32 s68, s74
	s_add_i32 s74, s74, s33
	s_cmpk_lt_i32 s74, 0x1601
	s_cselect_b64 s[66:67], -1, 0
	s_and_b64 s[66:67], s[44:45], s[66:67]
	s_and_b64 s[66:67], s[66:67], exec
	s_cselect_b32 s66, s86, s91
	s_add_i32 s68, s66, s68
	s_cmpk_gt_i32 s68, 0x15ff
	s_mov_b64 s[66:67], -1
	s_cbranch_scc1 .LBB0_272
	s_mul_hi_i32 s66, s68, 0x2e8ba2e9
	s_lshr_b32 s67, s66, 31
	s_ashr_i32 s66, s66, 6
	s_add_i32 s66, s66, s67
	s_mul_i32 s67, s66, 0x160
	s_sub_i32 s67, s68, s67
	s_sext_i32_i16 s68, s67
	s_bfe_u32 s68, s68, 0x3001c
	s_add_i32 s68, s67, s68
	s_sext_i32_i16 s69, s68
	s_and_b32 s68, s68, 0xfff8
	s_sub_i32 s67, s67, s68
	s_ashr_i32 s76, s69, 3
	s_sext_i32_i16 s67, s67
	s_lshl_b32 s72, s76, 8
	s_lshl_b32 s66, s66, 11
	s_lshl_b32 s67, s67, 8
	s_ashr_i32 s73, s72, 31
	s_add_i32 s66, s67, s66
	s_lshl_b64 s[68:69], s[72:73], 12
	s_add_u32 s68, s6, s68
	s_addc_u32 s69, s7, s69
	v_readfirstlane_b32 s67, v136
	v_lshl_add_u64 v[0:1], s[68:69], 0, v[128:129]
	s_mov_b32 m0, s67
	v_readfirstlane_b32 s67, v137
	global_load_lds_dwordx4 v[0:1], off
	s_mov_b32 m0, s67
	s_ashr_i32 s67, s66, 31
	s_lshl_b64 s[70:71], s[66:67], 12
	s_add_u32 s78, s14, s70
	s_addc_u32 s79, s43, s71
	s_bitset1_b32 s72, 7
	s_ashr_i32 s73, s72, 31
	v_lshl_add_u64 v[2:3], v[0:1], 0, s[10:11]
	v_readfirstlane_b32 s67, v138
	s_lshl_b64 s[72:73], s[72:73], 12
	global_load_lds_dwordx4 v[2:3], off
	v_lshl_add_u64 v[2:3], s[78:79], 0, v[128:129]
	s_mov_b32 m0, s67
	v_readfirstlane_b32 s67, v139
	s_add_u32 s72, s6, s72
	global_load_lds_dwordx4 v[2:3], off
	v_lshl_add_u64 v[4:5], v[2:3], 0, s[10:11]
	s_mov_b32 m0, s67
	s_addc_u32 s73, s7, s73
	global_load_lds_dwordx4 v[4:5], off
	v_lshl_add_u64 v[4:5], s[72:73], 0, v[128:129]
	s_or_b32 s72, s66, 0x80
	s_ashr_i32 s73, s72, 31
	v_readfirstlane_b32 s67, v140
	s_lshl_b64 s[72:73], s[72:73], 12
	s_mov_b32 m0, s67
	v_readfirstlane_b32 s67, v141
	s_add_u32 s72, s14, s72
	global_load_lds_dwordx4 v[4:5], off
	v_lshl_add_u64 v[6:7], v[4:5], 0, s[10:11]
	s_mov_b32 m0, s67
	s_addc_u32 s73, s43, s73
	v_readfirstlane_b32 s67, v142
	global_load_lds_dwordx4 v[6:7], off
	v_lshl_add_u64 v[132:133], s[72:73], 0, v[128:129]
	s_mov_b32 m0, s67
	v_readfirstlane_b32 s67, v143
	global_load_lds_dwordx4 v[132:133], off
	v_lshl_add_u64 v[6:7], v[132:133], 0, s[10:11]
	s_mov_b32 m0, s67
	s_nop 0
	global_load_lds_dwordx4 v[6:7], off
	v_mov_b32_e32 v8, 0
	v_mov_b32_e32 v9, 0
	v_mov_b32_e32 v10, 0
	v_mov_b32_e32 v11, 0
	v_mov_b32_e32 v12, 0
	v_mov_b32_e32 v13, 0
	v_mov_b32_e32 v14, 0
	v_mov_b32_e32 v15, 0
	v_mov_b32_e32 v16, 0
	v_mov_b32_e32 v17, 0
	v_mov_b32_e32 v18, 0
	v_mov_b32_e32 v19, 0
	v_mov_b32_e32 v20, 0
	v_mov_b32_e32 v21, 0
	v_mov_b32_e32 v22, 0
	v_mov_b32_e32 v23, 0
	v_mov_b32_e32 v24, 0
	v_mov_b32_e32 v25, 0
	v_mov_b32_e32 v26, 0
	v_mov_b32_e32 v27, 0
	v_mov_b32_e32 v28, 0
	v_mov_b32_e32 v29, 0
	v_mov_b32_e32 v30, 0
	v_mov_b32_e32 v31, 0
	v_mov_b32_e32 v32, 0
	v_mov_b32_e32 v33, 0
	v_mov_b32_e32 v34, 0
	v_mov_b32_e32 v35, 0
	v_mov_b32_e32 v36, 0
	v_mov_b32_e32 v37, 0
	v_mov_b32_e32 v38, 0
	v_mov_b32_e32 v39, 0
	v_mov_b32_e32 v40, 0
	v_mov_b32_e32 v41, 0
	v_mov_b32_e32 v42, 0
	v_mov_b32_e32 v43, 0
	v_mov_b32_e32 v44, 0
	v_mov_b32_e32 v45, 0
	v_mov_b32_e32 v46, 0
	v_mov_b32_e32 v47, 0
	v_mov_b32_e32 v48, 0
	v_mov_b32_e32 v49, 0
	v_mov_b32_e32 v50, 0
	v_mov_b32_e32 v51, 0
	v_mov_b32_e32 v52, 0
	v_mov_b32_e32 v53, 0
	v_mov_b32_e32 v54, 0
	v_mov_b32_e32 v55, 0
	v_mov_b32_e32 v56, 0
	v_mov_b32_e32 v57, 0
	v_mov_b32_e32 v58, 0
	v_mov_b32_e32 v59, 0
	v_mov_b32_e32 v60, 0
	v_mov_b32_e32 v61, 0
	v_mov_b32_e32 v62, 0
	v_mov_b32_e32 v63, 0
	v_mov_b32_e32 v64, 0
	v_mov_b32_e32 v65, 0
	v_mov_b32_e32 v66, 0
	v_mov_b32_e32 v67, 0
	v_mov_b32_e32 v68, 0
	v_mov_b32_e32 v69, 0
	v_mov_b32_e32 v70, 0
	v_mov_b32_e32 v71, 0
	v_mov_b32_e32 v72, 0
	v_mov_b32_e32 v73, 0
	v_mov_b32_e32 v74, 0
	v_mov_b32_e32 v75, 0
	v_mov_b32_e32 v76, 0
	v_mov_b32_e32 v77, 0
	v_mov_b32_e32 v78, 0
	v_mov_b32_e32 v79, 0
	v_mov_b32_e32 v80, 0
	v_mov_b32_e32 v81, 0
	v_mov_b32_e32 v82, 0
	v_mov_b32_e32 v83, 0
	v_mov_b32_e32 v84, 0
	v_mov_b32_e32 v85, 0
	v_mov_b32_e32 v86, 0
	v_mov_b32_e32 v87, 0
	v_mov_b32_e32 v88, 0
	v_mov_b32_e32 v89, 0
	v_mov_b32_e32 v90, 0
	v_mov_b32_e32 v91, 0
	v_mov_b32_e32 v92, 0
	v_mov_b32_e32 v93, 0
	v_mov_b32_e32 v94, 0
	v_mov_b32_e32 v95, 0
	v_mov_b32_e32 v96, 0
	v_mov_b32_e32 v97, 0
	v_mov_b32_e32 v98, 0
	v_mov_b32_e32 v99, 0
	v_mov_b32_e32 v100, 0
	v_mov_b32_e32 v101, 0
	v_mov_b32_e32 v102, 0
	v_mov_b32_e32 v103, 0
	v_mov_b32_e32 v104, 0
	v_mov_b32_e32 v105, 0
	v_mov_b32_e32 v106, 0
	v_mov_b32_e32 v107, 0
	v_mov_b32_e32 v108, 0
	v_mov_b32_e32 v109, 0
	v_mov_b32_e32 v110, 0
	v_mov_b32_e32 v111, 0
	v_mov_b32_e32 v112, 0
	v_mov_b32_e32 v113, 0
	v_mov_b32_e32 v114, 0
	v_mov_b32_e32 v115, 0
	v_mov_b32_e32 v116, 0
	v_mov_b32_e32 v117, 0
	v_mov_b32_e32 v118, 0
	v_mov_b32_e32 v119, 0
	v_mov_b32_e32 v120, 0
	v_mov_b32_e32 v121, 0
	v_mov_b32_e32 v122, 0
	v_mov_b32_e32 v123, 0
	v_mov_b32_e32 v124, 0
	v_mov_b32_e32 v125, 0
	v_mov_b32_e32 v126, 0
	v_mov_b32_e32 v127, 0
	s_and_saveexec_b64 s[72:73], s[4:5]
	s_cbranch_execz .LBB0_276
	s_barrier
.LBB0_276:
	s_or_b64 exec, exec, s[72:73]
	v_readfirstlane_b32 s67, v144
	v_lshl_add_u64 v[6:7], v[0:1], 0, s[12:13]
	s_mov_b32 m0, s67
	v_readfirstlane_b32 s67, v145
	s_waitcnt vmcnt(4)
	s_barrier
	global_load_lds_dwordx4 v[6:7], off
	v_lshl_add_u64 v[0:1], v[0:1], 0, s[16:17]
	s_mov_b32 m0, s67
	v_readfirstlane_b32 s67, v146
	global_load_lds_dwordx4 v[0:1], off
	v_lshl_add_u64 v[0:1], v[2:3], 0, s[12:13]
	s_mov_b32 m0, s67
	v_readfirstlane_b32 s67, v147
	global_load_lds_dwordx4 v[0:1], off
	v_lshl_add_u64 v[0:1], v[2:3], 0, s[16:17]
	s_mov_b32 m0, s67
	v_readfirstlane_b32 s67, v148
	global_load_lds_dwordx4 v[0:1], off
	v_lshl_add_u64 v[0:1], v[4:5], 0, s[12:13]
	s_mov_b32 m0, s67
	v_readfirstlane_b32 s67, v149
	global_load_lds_dwordx4 v[0:1], off
	v_lshl_add_u64 v[0:1], v[4:5], 0, s[16:17]
	s_mov_b32 m0, s67
	s_add_u32 s70, s6, s70
	global_load_lds_dwordx4 v[0:1], off
	v_mov_b32_e32 v0, 0
	s_addc_u32 s71, s7, s71
	s_mov_b32 s67, -2
	v_mov_b32_e32 v1, v0
	v_mov_b32_e32 v2, v0
	v_mov_b32_e32 v3, v0
	v_mov_b32_e32 v4, v0
	v_mov_b32_e32 v5, v0
	v_mov_b32_e32 v6, v0
	v_mov_b32_e32 v7, v0
	s_waitcnt vmcnt(6)
	s_barrier

; #define STAGE(P, BASE, br, kt) do { const char* _gb = (const char*)(BASE) + ((size_t)(br) * K + (size_t)(kt) * BK) * 2; \
;     __builtin_amdgcn_global_load_lds((const unsigned*)(_gb + loff0), (unsigned*)((char*)(P) + tid * 16), 16, 0, 0); \
;     __builtin_amdgcn_global_load_lds((const unsigned*)(_gb + (size_t)K * 128 + loff0), (unsigned*)((char*)(P) + tid * 16 + 8192), 16, 0, 0); } while (0)
; #define WAIT_V(n) asm volatile("s_waitcnt vmcnt(" #n ")" ::: "memory")
; #define BAR __builtin_amdgcn_s_barrier()
; template <int EPI> ...
;     ...
;   f32x4 acc[2][2][4][2] = {};
;   bf16x8 At[4][2], B0[2][2], B1[2][2];
;   int nt = K / BK;
;   const int aoff0 = lds_byte(wr * 64 + fr, fq * 8), aoff1 = lds_byte(wr * 64 + fr, 32 + fq * 8);
;   const int brw = wc * 32 + (fr >> 2) * 8 + (fr & 3);
;   const int boff0 = lds_byte(brw, fq * 8), boff1 = lds_byte(brw, 32 + fq * 8);
;   unsigned loff0;
;   { int _r, _c; stage_rc(tid * 16, _r, _c); loff0 = (unsigned)(_r * K + _c) * 2u; }
;   STAGE(SB(0, 0), Bt, bcol, 0); STAGE(SA(0, 0), A, brow, 0);
;   STAGE(SB(0, 1), Bt, bcol + HALF, 0); STAGE(SA(0, 1), A, brow + HALF, 0);
;   if (wr == 1) BAR;
;   WAIT_V(4); BAR;
;   STAGE(SB(1, 0), Bt, bcol, 1); STAGE(SA(1, 0), A, brow, 1); STAGE(SB(1, 1), Bt, bcol + HALF, 1);
;   WAIT_V(6); BAR;
.LBB0_320:
	s_mov_b32 s62, s72
	s_add_i32 s72, s72, s33
	s_cmpk_lt_i32 s72, 0x401
	s_cselect_b64 s[60:61], -1, 0
	s_and_b64 s[60:61], s[44:45], s[60:61]
	s_and_b64 s[60:61], s[60:61], exec
	s_cselect_b32 s60, s86, s91
	s_add_i32 s62, s60, s62
	s_cmpk_gt_i32 s62, 0x3ff
	s_mov_b64 s[60:61], -1
	s_cbranch_scc1 .LBB0_319
	s_sub_i32 s62, 0x3ff, s62
	s_ashr_i32 s60, s62, 31
	s_lshr_b32 s60, s60, 26
	s_add_i32 s60, s62, s60
	s_and_b32 s61, s60, 0xffc0
	s_sub_i32 s61, s62, s61
	s_bfe_i32 s62, s61, 0x80000
	s_bfe_u32 s62, s62, 0x3000c
	s_add_i32 s62, s61, s62
	s_bfe_i32 s63, s62, 0x80000
	s_and_b32 s62, s62, 0xf8
	s_sub_i32 s61, s61, s62
	s_sext_i32_i16 s63, s63
	s_sext_i32_i8 s61, s61
	s_lshl_b32 s60, s60, 5
	s_ashr_i32 s64, s63, 3
	s_and_b32 s60, s60, 0xfffff800
	s_lshl_b32 s73, s61, 8
	s_add_i32 s73, s73, s60
	s_lshl_b32 s60, s64, 8
	s_mul_i32 s66, s64, 0x2c0000
	s_mul_hi_i32 s67, s60, 0x2c00
	s_add_u32 s62, s68, s66
	s_addc_u32 s63, s69, s67
	v_readfirstlane_b32 s61, v135
	s_mul_i32 s77, s73, 0x2c00
	v_lshl_add_u64 v[0:1], s[62:63], 0, v[128:129]
	s_mov_b32 m0, s61
	v_readfirstlane_b32 s61, v136
	s_mul_hi_i32 s76, s73, 0x2c00
	s_add_u32 s62, s14, s77
	global_load_lds_dwordx4 v[0:1], off
	v_lshl_add_u64 v[2:3], v[0:1], 0, s[8:9]
	s_mov_b32 m0, s61
	s_addc_u32 s63, s43, s76
	global_load_lds_dwordx4 v[2:3], off
	v_lshl_add_u64 v[2:3], s[62:63], 0, v[128:129]
	s_mul_i32 s62, s64, 0x160000
	v_readfirstlane_b32 s61, v137
	s_ashr_i32 s63, s62, 31
	s_mov_b32 m0, s61
	v_readfirstlane_b32 s61, v138
	s_lshl_b64 s[62:63], s[62:63], 1
	global_load_lds_dwordx4 v[2:3], off
	s_mov_b32 m0, s61
	s_add_u32 s61, s68, s62
	s_addc_u32 s65, s69, s63
	s_add_u32 s64, s61, 0x160000
	v_lshl_add_u64 v[4:5], v[2:3], 0, s[8:9]
	s_addc_u32 s65, s65, 0
	v_readfirstlane_b32 s61, v139
	global_load_lds_dwordx4 v[4:5], off
	v_lshl_add_u64 v[4:5], s[64:65], 0, v[128:129]
	s_mov_b32 m0, s61
	v_readfirstlane_b32 s61, v140
	global_load_lds_dwordx4 v[4:5], off
	s_mov_b32 m0, s61
	s_or_b32 s61, s73, 0x80
	s_mul_i32 s75, s61, 0x2c00
	s_mul_hi_i32 s74, s61, 0x2c00
	s_add_u32 s64, s14, s75
	v_lshl_add_u64 v[6:7], v[4:5], 0, s[8:9]
	s_addc_u32 s65, s43, s74
	v_readfirstlane_b32 s61, v141
	global_load_lds_dwordx4 v[6:7], off
	v_lshl_add_u64 v[6:7], s[64:65], 0, v[128:129]
	s_mov_b32 m0, s61
	v_readfirstlane_b32 s61, v142
	global_load_lds_dwordx4 v[6:7], off
	v_lshl_add_u64 v[6:7], v[6:7], 0, s[8:9]
	s_mov_b32 m0, s61
	s_nop 0
	global_load_lds_dwordx4 v[6:7], off
	v_mov_b32_e32 v8, 0
	v_mov_b32_e32 v9, 0
	v_mov_b32_e32 v10, 0
	v_mov_b32_e32 v11, 0
	v_mov_b32_e32 v12, 0
	v_mov_b32_e32 v13, 0
	v_mov_b32_e32 v14, 0
	v_mov_b32_e32 v15, 0
	v_mov_b32_e32 v16, 0
	v_mov_b32_e32 v17, 0
	v_mov_b32_e32 v18, 0
	v_mov_b32_e32 v19, 0
	v_mov_b32_e32 v20, 0
	v_mov_b32_e32 v21, 0
	v_mov_b32_e32 v22, 0
	v_mov_b32_e32 v23, 0
	v_mov_b32_e32 v24, 0
	v_mov_b32_e32 v25, 0
	v_mov_b32_e32 v26, 0
	v_mov_b32_e32 v27, 0
	v_mov_b32_e32 v28, 0
	v_mov_b32_e32 v29, 0
	v_mov_b32_e32 v30, 0
	v_mov_b32_e32 v31, 0
	v_mov_b32_e32 v32, 0
	v_mov_b32_e32 v33, 0
	v_mov_b32_e32 v34, 0
	v_mov_b32_e32 v35, 0
	v_mov_b32_e32 v36, 0
	v_mov_b32_e32 v37, 0
	v_mov_b32_e32 v38, 0
	v_mov_b32_e32 v39, 0
	v_mov_b32_e32 v40, 0
	v_mov_b32_e32 v41, 0
	v_mov_b32_e32 v42, 0
	v_mov_b32_e32 v43, 0
	v_mov_b32_e32 v44, 0
	v_mov_b32_e32 v45, 0
	v_mov_b32_e32 v46, 0
	v_mov_b32_e32 v47, 0
	v_mov_b32_e32 v48, 0
	v_mov_b32_e32 v49, 0
	v_mov_b32_e32 v50, 0
	v_mov_b32_e32 v51, 0
	v_mov_b32_e32 v52, 0
	v_mov_b32_e32 v53, 0
	v_mov_b32_e32 v54, 0
	v_mov_b32_e32 v55, 0
	v_mov_b32_e32 v56, 0
	v_mov_b32_e32 v57, 0
	v_mov_b32_e32 v58, 0
	v_mov_b32_e32 v59, 0
	v_mov_b32_e32 v60, 0
	v_mov_b32_e32 v61, 0
	v_mov_b32_e32 v62, 0
	v_mov_b32_e32 v63, 0
	v_mov_b32_e32 v64, 0
	v_mov_b32_e32 v65, 0
	v_mov_b32_e32 v66, 0
	v_mov_b32_e32 v67, 0
	v_mov_b32_e32 v68, 0
	v_mov_b32_e32 v69, 0
	v_mov_b32_e32 v70, 0
	v_mov_b32_e32 v71, 0
	v_mov_b32_e32 v72, 0
	v_mov_b32_e32 v73, 0
	v_mov_b32_e32 v74, 0
	v_mov_b32_e32 v75, 0
	v_mov_b32_e32 v76, 0
	v_mov_b32_e32 v77, 0
	v_mov_b32_e32 v78, 0
	v_mov_b32_e32 v79, 0
	v_mov_b32_e32 v80, 0
	v_mov_b32_e32 v81, 0
	v_mov_b32_e32 v82, 0
	v_mov_b32_e32 v83, 0
	v_mov_b32_e32 v84, 0
	v_mov_b32_e32 v85, 0
	v_mov_b32_e32 v86, 0
	v_mov_b32_e32 v87, 0
	v_mov_b32_e32 v88, 0
	v_mov_b32_e32 v89, 0
	v_mov_b32_e32 v90, 0
	v_mov_b32_e32 v91, 0
	v_mov_b32_e32 v92, 0
	v_mov_b32_e32 v93, 0
	v_mov_b32_e32 v94, 0
	v_mov_b32_e32 v95, 0
	v_mov_b32_e32 v96, 0
	v_mov_b32_e32 v97, 0
	v_mov_b32_e32 v98, 0
	v_mov_b32_e32 v99, 0
	v_mov_b32_e32 v100, 0
	v_mov_b32_e32 v101, 0
	v_mov_b32_e32 v102, 0
	v_mov_b32_e32 v103, 0
	v_mov_b32_e32 v104, 0
	v_mov_b32_e32 v105, 0
	v_mov_b32_e32 v106, 0
	v_mov_b32_e32 v107, 0
	v_mov_b32_e32 v108, 0
	v_mov_b32_e32 v109, 0
	v_mov_b32_e32 v110, 0
	v_mov_b32_e32 v111, 0
	v_mov_b32_e32 v112, 0
	v_mov_b32_e32 v113, 0
	v_mov_b32_e32 v114, 0
	v_mov_b32_e32 v115, 0
	v_mov_b32_e32 v116, 0
	v_mov_b32_e32 v117, 0
	v_mov_b32_e32 v118, 0
	v_mov_b32_e32 v119, 0
	v_mov_b32_e32 v120, 0
	v_mov_b32_e32 v121, 0
	v_mov_b32_e32 v122, 0
	v_mov_b32_e32 v123, 0
	v_mov_b32_e32 v124, 0
	v_mov_b32_e32 v125, 0
	v_mov_b32_e32 v126, 0
	v_mov_b32_e32 v127, 0
	s_and_saveexec_b64 s[64:65], s[4:5]
	s_cbranch_execz .LBB0_323
	s_barrier
.LBB0_323:
	s_or_b64 exec, exec, s[64:65]
	v_readfirstlane_b32 s64, v143
	v_lshl_add_u64 v[6:7], v[0:1], 0, s[10:11]
	s_mov_b32 m0, s64
	v_readfirstlane_b32 s64, v144
	s_waitcnt vmcnt(4)
	s_barrier
	global_load_lds_dwordx4 v[6:7], off
	v_lshl_add_u64 v[0:1], v[0:1], 0, s[12:13]
	s_mov_b32 m0, s64
	v_readfirstlane_b32 s64, v145
	global_load_lds_dwordx4 v[0:1], off
	v_lshl_add_u64 v[0:1], v[2:3], 0, s[10:11]
	s_mov_b32 m0, s64
	v_readfirstlane_b32 s64, v146
	global_load_lds_dwordx4 v[0:1], off
	v_lshl_add_u64 v[0:1], v[2:3], 0, s[12:13]
	s_mov_b32 m0, s64
	v_readfirstlane_b32 s64, v147
	global_load_lds_dwordx4 v[0:1], off
	v_lshl_add_u64 v[0:1], v[4:5], 0, s[10:11]
	s_mov_b32 m0, s64
	v_readfirstlane_b32 s64, v148
	global_load_lds_dwordx4 v[0:1], off
	v_lshl_add_u64 v[0:1], v[4:5], 0, s[12:13]
	s_mov_b32 m0, s64
	s_ashr_i32 s61, s60, 31
	global_load_lds_dwordx4 v[0:1], off
	s_add_u32 s62, s6, s62
	s_addc_u32 s63, s7, s63
	s_add_u32 s64, s6, s77
	s_addc_u32 s65, s7, s76
	s_add_u32 s66, s6, s66
	v_mov_b32_e32 v0, 0
	s_addc_u32 s67, s7, s67
	s_mov_b32 s76, -2
	v_mov_b32_e32 v1, v0
	v_mov_b32_e32 v2, v0
	v_mov_b32_e32 v3, v0
	v_mov_b32_e32 v4, v0
	v_mov_b32_e32 v5, v0
	v_mov_b32_e32 v6, v0
	v_mov_b32_e32 v7, v0
	s_waitcnt vmcnt(6)
	s_barrier

; #define STAGE(P, BASE, br, kt) do { const char* _gb = (const char*)(BASE) + ((size_t)(br) * K + (size_t)(kt) * BK) * 2; \
;     __builtin_amdgcn_global_load_lds((const unsigned*)(_gb + loff0), (unsigned*)((char*)(P) + tid * 16), 16, 0, 0); \
;     __builtin_amdgcn_global_load_lds((const unsigned*)(_gb + (size_t)K * 128 + loff0), (unsigned*)((char*)(P) + tid * 16 + 8192), 16, 0, 0); } while (0)
; #define WAIT_V(n) asm volatile("s_waitcnt vmcnt(" #n ")" ::: "memory")
; #define BAR __builtin_amdgcn_s_barrier()
; template <int EPI> ...
;     ...
;   f32x4 acc[2][2][4][2] = {};
;   bf16x8 At[4][2], B0[2][2], B1[2][2];
;   int nt = K / BK;
;   const int aoff0 = lds_byte(wr * 64 + fr, fq * 8), aoff1 = lds_byte(wr * 64 + fr, 32 + fq * 8);
;   const int brw = wc * 32 + (fr >> 2) * 8 + (fr & 3);
;   const int boff0 = lds_byte(brw, fq * 8), boff1 = lds_byte(brw, 32 + fq * 8);
;   unsigned loff0;
;   { int _r, _c; stage_rc(tid * 16, _r, _c); loff0 = (unsigned)(_r * K + _c) * 2u; }
;   STAGE(SB(0, 0), Bt, bcol, 0); STAGE(SA(0, 0), A, brow, 0);
;   STAGE(SB(0, 1), Bt, bcol + HALF, 0); STAGE(SA(0, 1), A, brow + HALF, 0);
;   if (wr == 1) BAR;
;   WAIT_V(4); BAR;
;   STAGE(SB(1, 0), Bt, bcol, 1); STAGE(SA(1, 0), A, brow, 1); STAGE(SB(1, 1), Bt, bcol + HALF, 1);
;   WAIT_V(6); BAR;
.LBB0_407:
	s_mov_b32 s62, s76
	s_add_i32 s76, s76, s33
	s_cmpk_lt_i32 s76, 0xb01
	s_cselect_b64 s[60:61], -1, 0
	s_and_b64 s[60:61], s[44:45], s[60:61]
	s_and_b64 s[60:61], s[60:61], exec
	s_cselect_b32 s60, s86, s91
	s_add_i32 s62, s60, s62
	s_cmpk_gt_i32 s62, 0xaff
	s_mov_b64 s[60:61], -1
	s_cbranch_scc1 .LBB0_406
	s_mul_hi_i32 s60, s62, 0x2e8ba2e9
	s_lshr_b32 s61, s60, 31
	s_ashr_i32 s60, s60, 5
	s_add_i32 s60, s60, s61
	s_mul_i32 s61, s60, 0xb0
	s_sub_i32 s61, s62, s61
	s_sext_i32_i16 s62, s61
	s_bfe_u32 s62, s62, 0x3001c
	s_add_i32 s62, s61, s62
	s_sext_i32_i16 s63, s62
	s_and_b32 s62, s62, 0xfff8
	s_sub_i32 s61, s61, s62
	s_sext_i32_i16 s61, s61
	s_lshl_b32 s60, s60, 11
	s_lshl_b32 s61, s61, 8
	s_add_i32 s60, s61, s60
	s_lshl_b32 s61, s63, 5
	s_and_b32 s62, s61, 0xffffff00
	s_ashr_i32 s63, s62, 31
	s_lshl_b64 s[66:67], s[62:63], 12
	s_add_u32 s64, s72, s66
	s_addc_u32 s65, s73, s67
	v_readfirstlane_b32 s61, v135
	v_lshl_add_u64 v[0:1], s[64:65], 0, v[128:129]
	s_mov_b32 m0, s61
	v_readfirstlane_b32 s61, v136
	global_load_lds_dwordx4 v[0:1], off
	s_mov_b32 m0, s61
	s_ashr_i32 s61, s60, 31
	s_lshl_b64 s[68:69], s[60:61], 12
	s_add_u32 s64, s14, s68
	v_lshl_add_u64 v[2:3], v[0:1], 0, s[8:9]
	s_addc_u32 s65, s43, s69
	global_load_lds_dwordx4 v[2:3], off
	v_lshl_add_u64 v[2:3], s[64:65], 0, v[128:129]
	s_or_b32 s64, s62, 0x80
	s_ashr_i32 s65, s64, 31
	v_readfirstlane_b32 s61, v137
	s_lshl_b64 s[64:65], s[64:65], 12
	s_mov_b32 m0, s61
	v_readfirstlane_b32 s61, v138
	s_add_u32 s64, s72, s64
	global_load_lds_dwordx4 v[2:3], off
	v_lshl_add_u64 v[4:5], v[2:3], 0, s[8:9]
	s_mov_b32 m0, s61
	s_addc_u32 s65, s73, s65
	global_load_lds_dwordx4 v[4:5], off
	v_lshl_add_u64 v[4:5], s[64:65], 0, v[128:129]
	s_or_b32 s64, s60, 0x80
	s_ashr_i32 s65, s64, 31
	v_readfirstlane_b32 s61, v139
	s_lshl_b64 s[64:65], s[64:65], 12
	s_mov_b32 m0, s61
	v_readfirstlane_b32 s61, v140
	s_add_u32 s70, s14, s64
	global_load_lds_dwordx4 v[4:5], off
	v_lshl_add_u64 v[6:7], v[4:5], 0, s[8:9]
	s_mov_b32 m0, s61
	s_addc_u32 s71, s43, s65
	v_readfirstlane_b32 s61, v141
	global_load_lds_dwordx4 v[6:7], off
	v_lshl_add_u64 v[6:7], s[70:71], 0, v[128:129]
	s_mov_b32 m0, s61
	v_readfirstlane_b32 s61, v142
	global_load_lds_dwordx4 v[6:7], off
	v_lshl_add_u64 v[6:7], v[6:7], 0, s[8:9]
	s_mov_b32 m0, s61
	s_nop 0
	global_load_lds_dwordx4 v[6:7], off
	v_mov_b32_e32 v8, 0
	v_mov_b32_e32 v9, 0
	v_mov_b32_e32 v10, 0
	v_mov_b32_e32 v11, 0
	v_mov_b32_e32 v12, 0
	v_mov_b32_e32 v13, 0
	v_mov_b32_e32 v14, 0
	v_mov_b32_e32 v15, 0
	v_mov_b32_e32 v16, 0
	v_mov_b32_e32 v17, 0
	v_mov_b32_e32 v18, 0
	v_mov_b32_e32 v19, 0
	v_mov_b32_e32 v20, 0
	v_mov_b32_e32 v21, 0
	v_mov_b32_e32 v22, 0
	v_mov_b32_e32 v23, 0
	v_mov_b32_e32 v24, 0
	v_mov_b32_e32 v25, 0
	v_mov_b32_e32 v26, 0
	v_mov_b32_e32 v27, 0
	v_mov_b32_e32 v28, 0
	v_mov_b32_e32 v29, 0
	v_mov_b32_e32 v30, 0
	v_mov_b32_e32 v31, 0
	v_mov_b32_e32 v32, 0
	v_mov_b32_e32 v33, 0
	v_mov_b32_e32 v34, 0
	v_mov_b32_e32 v35, 0
	v_mov_b32_e32 v36, 0
	v_mov_b32_e32 v37, 0
	v_mov_b32_e32 v38, 0
	v_mov_b32_e32 v39, 0
	v_mov_b32_e32 v40, 0
	v_mov_b32_e32 v41, 0
	v_mov_b32_e32 v42, 0
	v_mov_b32_e32 v43, 0
	v_mov_b32_e32 v44, 0
	v_mov_b32_e32 v45, 0
	v_mov_b32_e32 v46, 0
	v_mov_b32_e32 v47, 0
	v_mov_b32_e32 v48, 0
	v_mov_b32_e32 v49, 0
	v_mov_b32_e32 v50, 0
	v_mov_b32_e32 v51, 0
	v_mov_b32_e32 v52, 0
	v_mov_b32_e32 v53, 0
	v_mov_b32_e32 v54, 0
	v_mov_b32_e32 v55, 0
	v_mov_b32_e32 v56, 0
	v_mov_b32_e32 v57, 0
	v_mov_b32_e32 v58, 0
	v_mov_b32_e32 v59, 0
	v_mov_b32_e32 v60, 0
	v_mov_b32_e32 v61, 0
	v_mov_b32_e32 v62, 0
	v_mov_b32_e32 v63, 0
	v_mov_b32_e32 v64, 0
	v_mov_b32_e32 v65, 0
	v_mov_b32_e32 v66, 0
	v_mov_b32_e32 v67, 0
	v_mov_b32_e32 v68, 0
	v_mov_b32_e32 v69, 0
	v_mov_b32_e32 v70, 0
	v_mov_b32_e32 v71, 0
	v_mov_b32_e32 v72, 0
	v_mov_b32_e32 v73, 0
	v_mov_b32_e32 v74, 0
	v_mov_b32_e32 v75, 0
	v_mov_b32_e32 v76, 0
	v_mov_b32_e32 v77, 0
	v_mov_b32_e32 v78, 0
	v_mov_b32_e32 v79, 0
	v_mov_b32_e32 v80, 0
	v_mov_b32_e32 v81, 0
	v_mov_b32_e32 v82, 0
	v_mov_b32_e32 v83, 0
	v_mov_b32_e32 v84, 0
	v_mov_b32_e32 v85, 0
	v_mov_b32_e32 v86, 0
	v_mov_b32_e32 v87, 0
	v_mov_b32_e32 v88, 0
	v_mov_b32_e32 v89, 0
	v_mov_b32_e32 v90, 0
	v_mov_b32_e32 v91, 0
	v_mov_b32_e32 v92, 0
	v_mov_b32_e32 v93, 0
	v_mov_b32_e32 v94, 0
	v_mov_b32_e32 v95, 0
	v_mov_b32_e32 v96, 0
	v_mov_b32_e32 v97, 0
	v_mov_b32_e32 v98, 0
	v_mov_b32_e32 v99, 0
	v_mov_b32_e32 v100, 0
	v_mov_b32_e32 v101, 0
	v_mov_b32_e32 v102, 0
	v_mov_b32_e32 v103, 0
	v_mov_b32_e32 v104, 0
	v_mov_b32_e32 v105, 0
	v_mov_b32_e32 v106, 0
	v_mov_b32_e32 v107, 0
	v_mov_b32_e32 v108, 0
	v_mov_b32_e32 v109, 0
	v_mov_b32_e32 v110, 0
	v_mov_b32_e32 v111, 0
	v_mov_b32_e32 v112, 0
	v_mov_b32_e32 v113, 0
	v_mov_b32_e32 v114, 0
	v_mov_b32_e32 v115, 0
	v_mov_b32_e32 v116, 0
	v_mov_b32_e32 v117, 0
	v_mov_b32_e32 v118, 0
	v_mov_b32_e32 v119, 0
	v_mov_b32_e32 v120, 0
	v_mov_b32_e32 v121, 0
	v_mov_b32_e32 v122, 0
	v_mov_b32_e32 v123, 0
	v_mov_b32_e32 v124, 0
	v_mov_b32_e32 v125, 0
	v_mov_b32_e32 v126, 0
	v_mov_b32_e32 v127, 0
	s_and_saveexec_b64 s[70:71], s[4:5]
	s_cbranch_execz .LBB0_410
	s_barrier
.LBB0_410:
	s_or_b64 exec, exec, s[70:71]
	v_readfirstlane_b32 s61, v143
	v_lshl_add_u64 v[6:7], v[0:1], 0, s[10:11]
	s_mov_b32 m0, s61
	v_readfirstlane_b32 s61, v144
	s_waitcnt vmcnt(4)
	s_barrier
	global_load_lds_dwordx4 v[6:7], off
	v_lshl_add_u64 v[0:1], v[0:1], 0, s[12:13]
	s_mov_b32 m0, s61
	v_readfirstlane_b32 s61, v145
	global_load_lds_dwordx4 v[0:1], off
	v_lshl_add_u64 v[0:1], v[2:3], 0, s[10:11]
	s_mov_b32 m0, s61
	v_readfirstlane_b32 s61, v146
	global_load_lds_dwordx4 v[0:1], off
	v_lshl_add_u64 v[0:1], v[2:3], 0, s[12:13]
	s_mov_b32 m0, s61
	v_readfirstlane_b32 s61, v147
	global_load_lds_dwordx4 v[0:1], off
	v_lshl_add_u64 v[0:1], v[4:5], 0, s[10:11]
	s_mov_b32 m0, s61
	v_readfirstlane_b32 s61, v148
	global_load_lds_dwordx4 v[0:1], off
	v_lshl_add_u64 v[0:1], v[4:5], 0, s[12:13]
	s_mov_b32 m0, s61
	s_add_u32 s66, s6, s66
	global_load_lds_dwordx4 v[0:1], off
	s_addc_u32 s67, s7, s67
	s_add_u32 s68, s6, s68
	v_mov_b32_e32 v0, 0
	s_addc_u32 s69, s7, s69
	s_mov_b32 s61, -2
	v_mov_b32_e32 v1, v0
	v_mov_b32_e32 v2, v0
	v_mov_b32_e32 v3, v0
	v_mov_b32_e32 v4, v0
	v_mov_b32_e32 v5, v0
	v_mov_b32_e32 v6, v0
	v_mov_b32_e32 v7, v0
	s_waitcnt vmcnt(6)
	s_barrier

; #define STAGE(P, BASE, br, kt) do { const char* _gb = (const char*)(BASE) + ((size_t)(br) * K + (size_t)(kt) * BK) * 2; \
;     __builtin_amdgcn_global_load_lds((const unsigned*)(_gb + loff0), (unsigned*)((char*)(P) + tid * 16), 16, 0, 0); \
;     __builtin_amdgcn_global_load_lds((const unsigned*)(_gb + (size_t)K * 128 + loff0), (unsigned*)((char*)(P) + tid * 16 + 8192), 16, 0, 0); } while (0)
; #define WAIT_V(n) asm volatile("s_waitcnt vmcnt(" #n ")" ::: "memory")
; #define BAR __builtin_amdgcn_s_barrier()
; template <int EPI> ...
;     ...
;   f32x4 acc[2][2][4][2] = {};
;   bf16x8 At[4][2], B0[2][2], B1[2][2];
;   int nt = K / BK;
;   const int aoff0 = lds_byte(wr * 64 + fr, fq * 8), aoff1 = lds_byte(wr * 64 + fr, 32 + fq * 8);
;   const int brw = wc * 32 + (fr >> 2) * 8 + (fr & 3);
;   const int boff0 = lds_byte(brw, fq * 8), boff1 = lds_byte(brw, 32 + fq * 8);
;   unsigned loff0;
;   { int _r, _c; stage_rc(tid * 16, _r, _c); loff0 = (unsigned)(_r * K + _c) * 2u; }
;   STAGE(SB(0, 0), Bt, bcol, 0); STAGE(SA(0, 0), A, brow, 0);
;   STAGE(SB(0, 1), Bt, bcol + HALF, 0); STAGE(SA(0, 1), A, brow + HALF, 0);
;   if (wr == 1) BAR;
;   WAIT_V(4); BAR;
;   STAGE(SB(1, 0), Bt, bcol, 1); STAGE(SA(1, 0), A, brow, 1); STAGE(SB(1, 1), Bt, bcol + HALF, 1);
;   WAIT_V(6); BAR;
.LBB0_1014:
	s_mov_b32 s60, s74
	s_add_i32 s74, s74, s33
	s_cmpk_lt_i32 s74, 0x401
	s_cselect_b64 s[58:59], -1, 0
	s_and_b64 s[58:59], s[44:45], s[58:59]
	s_and_b64 s[58:59], s[58:59], exec
	s_cselect_b32 s58, s86, s91
	s_add_i32 s60, s58, s60
	s_cmpk_gt_i32 s60, 0x3ff
	s_mov_b64 s[58:59], -1
	s_cbranch_scc1 .LBB0_1013
	s_sub_i32 s60, 0x3ff, s60
	s_ashr_i32 s58, s60, 31
	s_lshr_b32 s58, s58, 26
	s_add_i32 s58, s60, s58
	s_and_b32 s59, s58, 0xffc0
	s_sub_i32 s59, s60, s59
	s_bfe_i32 s60, s59, 0x80000
	s_bfe_u32 s60, s60, 0x3000c
	s_add_i32 s60, s59, s60
	s_bfe_i32 s61, s60, 0x80000
	s_and_b32 s60, s60, 0xf8
	s_sub_i32 s59, s59, s60
	s_sext_i32_i8 s59, s59
	s_lshl_b32 s58, s58, 5
	s_sext_i32_i16 s61, s61
	s_and_b32 s58, s58, 0xfffff800
	s_lshl_b32 s59, s59, 8
	s_add_i32 s58, s59, s58
	s_lshl_b32 s59, s61, 5
	s_and_b32 s60, s59, 0xffffff00
	s_ashr_i32 s61, s60, 31
	s_lshl_b64 s[64:65], s[60:61], 12
	s_add_u32 s62, s70, s64
	s_addc_u32 s63, s71, s65
	v_readfirstlane_b32 s59, v135
	v_lshl_add_u64 v[0:1], s[62:63], 0, v[128:129]
	s_mov_b32 m0, s59
	v_readfirstlane_b32 s59, v136
	global_load_lds_dwordx4 v[0:1], off
	s_mov_b32 m0, s59
	s_ashr_i32 s59, s58, 31
	s_lshl_b64 s[66:67], s[58:59], 12
	s_add_u32 s62, s14, s66
	v_lshl_add_u64 v[2:3], v[0:1], 0, s[8:9]
	s_addc_u32 s63, s43, s67
	global_load_lds_dwordx4 v[2:3], off
	v_lshl_add_u64 v[2:3], s[62:63], 0, v[128:129]
	s_or_b32 s62, s60, 0x80
	s_ashr_i32 s63, s62, 31
	v_readfirstlane_b32 s59, v137
	s_lshl_b64 s[62:63], s[62:63], 12
	s_mov_b32 m0, s59
	v_readfirstlane_b32 s59, v138
	s_add_u32 s62, s70, s62
	global_load_lds_dwordx4 v[2:3], off
	v_lshl_add_u64 v[4:5], v[2:3], 0, s[8:9]
	s_mov_b32 m0, s59
	s_addc_u32 s63, s71, s63
	global_load_lds_dwordx4 v[4:5], off
	v_lshl_add_u64 v[4:5], s[62:63], 0, v[128:129]
	s_or_b32 s62, s58, 0x80
	s_ashr_i32 s63, s62, 31
	v_readfirstlane_b32 s59, v139
	s_lshl_b64 s[62:63], s[62:63], 12
	s_mov_b32 m0, s59
	v_readfirstlane_b32 s59, v140
	s_add_u32 s68, s14, s62
	global_load_lds_dwordx4 v[4:5], off
	v_lshl_add_u64 v[6:7], v[4:5], 0, s[8:9]
	s_mov_b32 m0, s59
	s_addc_u32 s69, s43, s63
	v_readfirstlane_b32 s59, v141
	global_load_lds_dwordx4 v[6:7], off
	v_lshl_add_u64 v[6:7], s[68:69], 0, v[128:129]
	s_mov_b32 m0, s59
	v_readfirstlane_b32 s59, v142
	global_load_lds_dwordx4 v[6:7], off
	v_lshl_add_u64 v[6:7], v[6:7], 0, s[8:9]
	s_mov_b32 m0, s59
	s_nop 0
	global_load_lds_dwordx4 v[6:7], off
	v_mov_b32_e32 v8, 0
	v_mov_b32_e32 v9, 0
	v_mov_b32_e32 v10, 0
	v_mov_b32_e32 v11, 0
	v_mov_b32_e32 v12, 0
	v_mov_b32_e32 v13, 0
	v_mov_b32_e32 v14, 0
	v_mov_b32_e32 v15, 0
	v_mov_b32_e32 v16, 0
	v_mov_b32_e32 v17, 0
	v_mov_b32_e32 v18, 0
	v_mov_b32_e32 v19, 0
	v_mov_b32_e32 v20, 0
	v_mov_b32_e32 v21, 0
	v_mov_b32_e32 v22, 0
	v_mov_b32_e32 v23, 0
	v_mov_b32_e32 v24, 0
	v_mov_b32_e32 v25, 0
	v_mov_b32_e32 v26, 0
	v_mov_b32_e32 v27, 0
	v_mov_b32_e32 v28, 0
	v_mov_b32_e32 v29, 0
	v_mov_b32_e32 v30, 0
	v_mov_b32_e32 v31, 0
	v_mov_b32_e32 v32, 0
	v_mov_b32_e32 v33, 0
	v_mov_b32_e32 v34, 0
	v_mov_b32_e32 v35, 0
	v_mov_b32_e32 v36, 0
	v_mov_b32_e32 v37, 0
	v_mov_b32_e32 v38, 0
	v_mov_b32_e32 v39, 0
	v_mov_b32_e32 v40, 0
	v_mov_b32_e32 v41, 0
	v_mov_b32_e32 v42, 0
	v_mov_b32_e32 v43, 0
	v_mov_b32_e32 v44, 0
	v_mov_b32_e32 v45, 0
	v_mov_b32_e32 v46, 0
	v_mov_b32_e32 v47, 0
	v_mov_b32_e32 v48, 0
	v_mov_b32_e32 v49, 0
	v_mov_b32_e32 v50, 0
	v_mov_b32_e32 v51, 0
	v_mov_b32_e32 v52, 0
	v_mov_b32_e32 v53, 0
	v_mov_b32_e32 v54, 0
	v_mov_b32_e32 v55, 0
	v_mov_b32_e32 v56, 0
	v_mov_b32_e32 v57, 0
	v_mov_b32_e32 v58, 0
	v_mov_b32_e32 v59, 0
	v_mov_b32_e32 v60, 0
	v_mov_b32_e32 v61, 0
	v_mov_b32_e32 v62, 0
	v_mov_b32_e32 v63, 0
	v_mov_b32_e32 v64, 0
	v_mov_b32_e32 v65, 0
	v_mov_b32_e32 v66, 0
	v_mov_b32_e32 v67, 0
	v_mov_b32_e32 v68, 0
	v_mov_b32_e32 v69, 0
	v_mov_b32_e32 v70, 0
	v_mov_b32_e32 v71, 0
	v_mov_b32_e32 v72, 0
	v_mov_b32_e32 v73, 0
	v_mov_b32_e32 v74, 0
	v_mov_b32_e32 v75, 0
	v_mov_b32_e32 v76, 0
	v_mov_b32_e32 v77, 0
	v_mov_b32_e32 v78, 0
	v_mov_b32_e32 v79, 0
	v_mov_b32_e32 v80, 0
	v_mov_b32_e32 v81, 0
	v_mov_b32_e32 v82, 0
	v_mov_b32_e32 v83, 0
	v_mov_b32_e32 v84, 0
	v_mov_b32_e32 v85, 0
	v_mov_b32_e32 v86, 0
	v_mov_b32_e32 v87, 0
	v_mov_b32_e32 v88, 0
	v_mov_b32_e32 v89, 0
	v_mov_b32_e32 v90, 0
	v_mov_b32_e32 v91, 0
	v_mov_b32_e32 v92, 0
	v_mov_b32_e32 v93, 0
	v_mov_b32_e32 v94, 0
	v_mov_b32_e32 v95, 0
	v_mov_b32_e32 v96, 0
	v_mov_b32_e32 v97, 0
	v_mov_b32_e32 v98, 0
	v_mov_b32_e32 v99, 0
	v_mov_b32_e32 v100, 0
	v_mov_b32_e32 v101, 0
	v_mov_b32_e32 v102, 0
	v_mov_b32_e32 v103, 0
	v_mov_b32_e32 v104, 0
	v_mov_b32_e32 v105, 0
	v_mov_b32_e32 v106, 0
	v_mov_b32_e32 v107, 0
	v_mov_b32_e32 v108, 0
	v_mov_b32_e32 v109, 0
	v_mov_b32_e32 v110, 0
	v_mov_b32_e32 v111, 0
	v_mov_b32_e32 v112, 0
	v_mov_b32_e32 v113, 0
	v_mov_b32_e32 v114, 0
	v_mov_b32_e32 v115, 0
	v_mov_b32_e32 v116, 0
	v_mov_b32_e32 v117, 0
	v_mov_b32_e32 v118, 0
	v_mov_b32_e32 v119, 0
	v_mov_b32_e32 v120, 0
	v_mov_b32_e32 v121, 0
	v_mov_b32_e32 v122, 0
	v_mov_b32_e32 v123, 0
	v_mov_b32_e32 v124, 0
	v_mov_b32_e32 v125, 0
	v_mov_b32_e32 v126, 0
	v_mov_b32_e32 v127, 0
	s_and_saveexec_b64 s[68:69], s[4:5]
	s_cbranch_execz .LBB0_1017
	s_barrier
.LBB0_1017:
	s_or_b64 exec, exec, s[68:69]
	v_readfirstlane_b32 s59, v143
	v_lshl_add_u64 v[6:7], v[0:1], 0, s[10:11]
	s_mov_b32 m0, s59
	v_readfirstlane_b32 s59, v144
	s_waitcnt vmcnt(4)
	s_barrier
	global_load_lds_dwordx4 v[6:7], off
	v_lshl_add_u64 v[0:1], v[0:1], 0, s[12:13]
	s_mov_b32 m0, s59
	v_readfirstlane_b32 s59, v145
	global_load_lds_dwordx4 v[0:1], off
	v_lshl_add_u64 v[0:1], v[2:3], 0, s[10:11]
	s_mov_b32 m0, s59
	v_readfirstlane_b32 s59, v146
	global_load_lds_dwordx4 v[0:1], off
	v_lshl_add_u64 v[0:1], v[2:3], 0, s[12:13]
	s_mov_b32 m0, s59
	v_readfirstlane_b32 s59, v147
	global_load_lds_dwordx4 v[0:1], off
	v_lshl_add_u64 v[0:1], v[4:5], 0, s[10:11]
	s_mov_b32 m0, s59
	v_readfirstlane_b32 s59, v148
	global_load_lds_dwordx4 v[0:1], off
	v_lshl_add_u64 v[0:1], v[4:5], 0, s[12:13]
	s_mov_b32 m0, s59
	s_add_u32 s64, s6, s64
	global_load_lds_dwordx4 v[0:1], off
	s_addc_u32 s65, s7, s65
	s_add_u32 s66, s6, s66
	v_mov_b32_e32 v0, 0
	s_addc_u32 s67, s7, s67
	s_mov_b32 s59, -2
	v_mov_b32_e32 v1, v0
	v_mov_b32_e32 v2, v0
	v_mov_b32_e32 v3, v0
	v_mov_b32_e32 v4, v0
	v_mov_b32_e32 v5, v0
	v_mov_b32_e32 v6, v0
	v_mov_b32_e32 v7, v0
	s_waitcnt vmcnt(6)
	s_barrier

; #define STAGE(P, BASE, br, kt) do { const char* _gb = (const char*)(BASE) + ((size_t)(br) * K + (size_t)(kt) * BK) * 2; \
;     __builtin_amdgcn_global_load_lds((const unsigned*)(_gb + loff0), (unsigned*)((char*)(P) + tid * 16), 16, 0, 0); \
;     __builtin_amdgcn_global_load_lds((const unsigned*)(_gb + (size_t)K * 128 + loff0), (unsigned*)((char*)(P) + tid * 16 + 8192), 16, 0, 0); } while (0)
; #define WAIT_V(n) asm volatile("s_waitcnt vmcnt(" #n ")" ::: "memory")
; #define BAR __builtin_amdgcn_s_barrier()
; template <int EPI> ...
;     ...
;   f32x4 acc[2][2][4][2] = {};
;   bf16x8 At[4][2], B0[2][2], B1[2][2];
;   int nt = K / BK;
;   const int aoff0 = lds_byte(wr * 64 + fr, fq * 8), aoff1 = lds_byte(wr * 64 + fr, 32 + fq * 8);
;   const int brw = wc * 32 + (fr >> 2) * 8 + (fr & 3);
;   const int boff0 = lds_byte(brw, fq * 8), boff1 = lds_byte(brw, 32 + fq * 8);
;   unsigned loff0;
;   { int _r, _c; stage_rc(tid * 16, _r, _c); loff0 = (unsigned)(_r * K + _c) * 2u; }
;   STAGE(SB(0, 0), Bt, bcol, 0); STAGE(SA(0, 0), A, brow, 0);
;   STAGE(SB(0, 1), Bt, bcol + HALF, 0); STAGE(SA(0, 1), A, brow + HALF, 0);
;   if (wr == 1) BAR;
;   WAIT_V(4); BAR;
;   STAGE(SB(1, 0), Bt, bcol, 1); STAGE(SA(1, 0), A, brow, 1); STAGE(SB(1, 1), Bt, bcol + HALF, 1);
;   WAIT_V(6); BAR;
.LBB0_1101:
	s_mov_b32 s66, s74
	s_add_i32 s74, s74, s33
	s_cmpk_lt_i32 s74, 0x1601
	s_cselect_b64 s[64:65], -1, 0
	s_and_b64 s[64:65], s[44:45], s[64:65]
	s_and_b64 s[64:65], s[64:65], exec
	s_cselect_b32 s64, s86, s91
	s_add_i32 s66, s64, s66
	s_cmpk_gt_i32 s66, 0x15ff
	s_mov_b64 s[64:65], -1
	s_cbranch_scc1 .LBB0_1100
	s_mul_hi_i32 s64, s66, 0x2e8ba2e9
	s_lshr_b32 s65, s64, 31
	s_ashr_i32 s64, s64, 6
	s_add_i32 s64, s64, s65
	s_mul_i32 s65, s64, 0x160
	s_sub_i32 s65, s66, s65
	s_sext_i32_i16 s66, s65
	s_bfe_u32 s66, s66, 0x3001c
	s_add_i32 s66, s65, s66
	s_sext_i32_i16 s67, s66
	s_and_b32 s66, s66, 0xfff8
	s_sub_i32 s65, s65, s66
	s_ashr_i32 s76, s67, 3
	s_sext_i32_i16 s65, s65
	s_lshl_b32 s70, s76, 8
	s_lshl_b32 s64, s64, 11
	s_lshl_b32 s65, s65, 8
	s_ashr_i32 s71, s70, 31
	s_add_i32 s64, s65, s64
	s_lshl_b64 s[68:69], s[70:71], 12
	s_add_u32 s66, s72, s68
	s_addc_u32 s67, s73, s69
	v_readfirstlane_b32 s65, v136
	v_lshl_add_u64 v[0:1], s[66:67], 0, v[128:129]
	s_mov_b32 m0, s65
	v_readfirstlane_b32 s65, v137
	global_load_lds_dwordx4 v[0:1], off
	s_mov_b32 m0, s65
	s_ashr_i32 s65, s64, 31
	s_lshl_b64 s[66:67], s[64:65], 12
	s_add_u32 s78, s14, s66
	s_addc_u32 s79, s43, s67
	s_bitset1_b32 s70, 7
	s_ashr_i32 s71, s70, 31
	v_lshl_add_u64 v[2:3], v[0:1], 0, s[10:11]
	v_readfirstlane_b32 s65, v138
	s_lshl_b64 s[70:71], s[70:71], 12
	global_load_lds_dwordx4 v[2:3], off
	v_lshl_add_u64 v[2:3], s[78:79], 0, v[128:129]
	s_mov_b32 m0, s65
	v_readfirstlane_b32 s65, v139
	s_add_u32 s70, s72, s70
	global_load_lds_dwordx4 v[2:3], off
	v_lshl_add_u64 v[4:5], v[2:3], 0, s[10:11]
	s_mov_b32 m0, s65
	s_addc_u32 s71, s73, s71
	global_load_lds_dwordx4 v[4:5], off
	v_lshl_add_u64 v[4:5], s[70:71], 0, v[128:129]
	s_or_b32 s70, s64, 0x80
	s_ashr_i32 s71, s70, 31
	v_readfirstlane_b32 s65, v140
	s_lshl_b64 s[70:71], s[70:71], 12
	s_mov_b32 m0, s65
	v_readfirstlane_b32 s65, v141
	s_add_u32 s70, s14, s70
	global_load_lds_dwordx4 v[4:5], off
	v_lshl_add_u64 v[6:7], v[4:5], 0, s[10:11]
	s_mov_b32 m0, s65
	s_addc_u32 s71, s43, s71
	v_readfirstlane_b32 s65, v142
	global_load_lds_dwordx4 v[6:7], off
	v_lshl_add_u64 v[132:133], s[70:71], 0, v[128:129]
	s_mov_b32 m0, s65
	v_readfirstlane_b32 s65, v143
	global_load_lds_dwordx4 v[132:133], off
	v_lshl_add_u64 v[6:7], v[132:133], 0, s[10:11]
	s_mov_b32 m0, s65
	s_nop 0
	global_load_lds_dwordx4 v[6:7], off
	v_mov_b32_e32 v8, 0
	v_mov_b32_e32 v9, 0
	v_mov_b32_e32 v10, 0
	v_mov_b32_e32 v11, 0
	v_mov_b32_e32 v12, 0
	v_mov_b32_e32 v13, 0
	v_mov_b32_e32 v14, 0
	v_mov_b32_e32 v15, 0
	v_mov_b32_e32 v16, 0
	v_mov_b32_e32 v17, 0
	v_mov_b32_e32 v18, 0
	v_mov_b32_e32 v19, 0
	v_mov_b32_e32 v20, 0
	v_mov_b32_e32 v21, 0
	v_mov_b32_e32 v22, 0
	v_mov_b32_e32 v23, 0
	v_mov_b32_e32 v24, 0
	v_mov_b32_e32 v25, 0
	v_mov_b32_e32 v26, 0
	v_mov_b32_e32 v27, 0
	v_mov_b32_e32 v28, 0
	v_mov_b32_e32 v29, 0
	v_mov_b32_e32 v30, 0
	v_mov_b32_e32 v31, 0
	v_mov_b32_e32 v32, 0
	v_mov_b32_e32 v33, 0
	v_mov_b32_e32 v34, 0
	v_mov_b32_e32 v35, 0
	v_mov_b32_e32 v36, 0
	v_mov_b32_e32 v37, 0
	v_mov_b32_e32 v38, 0
	v_mov_b32_e32 v39, 0
	v_mov_b32_e32 v40, 0
	v_mov_b32_e32 v41, 0
	v_mov_b32_e32 v42, 0
	v_mov_b32_e32 v43, 0
	v_mov_b32_e32 v44, 0
	v_mov_b32_e32 v45, 0
	v_mov_b32_e32 v46, 0
	v_mov_b32_e32 v47, 0
	v_mov_b32_e32 v48, 0
	v_mov_b32_e32 v49, 0
	v_mov_b32_e32 v50, 0
	v_mov_b32_e32 v51, 0
	v_mov_b32_e32 v52, 0
	v_mov_b32_e32 v53, 0
	v_mov_b32_e32 v54, 0
	v_mov_b32_e32 v55, 0
	v_mov_b32_e32 v56, 0
	v_mov_b32_e32 v57, 0
	v_mov_b32_e32 v58, 0
	v_mov_b32_e32 v59, 0
	v_mov_b32_e32 v60, 0
	v_mov_b32_e32 v61, 0
	v_mov_b32_e32 v62, 0
	v_mov_b32_e32 v63, 0
	v_mov_b32_e32 v64, 0
	v_mov_b32_e32 v65, 0
	v_mov_b32_e32 v66, 0
	v_mov_b32_e32 v67, 0
	v_mov_b32_e32 v68, 0
	v_mov_b32_e32 v69, 0
	v_mov_b32_e32 v70, 0
	v_mov_b32_e32 v71, 0
	v_mov_b32_e32 v72, 0
	v_mov_b32_e32 v73, 0
	v_mov_b32_e32 v74, 0
	v_mov_b32_e32 v75, 0
	v_mov_b32_e32 v76, 0
	v_mov_b32_e32 v77, 0
	v_mov_b32_e32 v78, 0
	v_mov_b32_e32 v79, 0
	v_mov_b32_e32 v80, 0
	v_mov_b32_e32 v81, 0
	v_mov_b32_e32 v82, 0
	v_mov_b32_e32 v83, 0
	v_mov_b32_e32 v84, 0
	v_mov_b32_e32 v85, 0
	v_mov_b32_e32 v86, 0
	v_mov_b32_e32 v87, 0
	v_mov_b32_e32 v88, 0
	v_mov_b32_e32 v89, 0
	v_mov_b32_e32 v90, 0
	v_mov_b32_e32 v91, 0
	v_mov_b32_e32 v92, 0
	v_mov_b32_e32 v93, 0
	v_mov_b32_e32 v94, 0
	v_mov_b32_e32 v95, 0
	v_mov_b32_e32 v96, 0
	v_mov_b32_e32 v97, 0
	v_mov_b32_e32 v98, 0
	v_mov_b32_e32 v99, 0
	v_mov_b32_e32 v100, 0
	v_mov_b32_e32 v101, 0
	v_mov_b32_e32 v102, 0
	v_mov_b32_e32 v103, 0
	v_mov_b32_e32 v104, 0
	v_mov_b32_e32 v105, 0
	v_mov_b32_e32 v106, 0
	v_mov_b32_e32 v107, 0
	v_mov_b32_e32 v108, 0
	v_mov_b32_e32 v109, 0
	v_mov_b32_e32 v110, 0
	v_mov_b32_e32 v111, 0
	v_mov_b32_e32 v112, 0
	v_mov_b32_e32 v113, 0
	v_mov_b32_e32 v114, 0
	v_mov_b32_e32 v115, 0
	v_mov_b32_e32 v116, 0
	v_mov_b32_e32 v117, 0
	v_mov_b32_e32 v118, 0
	v_mov_b32_e32 v119, 0
	v_mov_b32_e32 v120, 0
	v_mov_b32_e32 v121, 0
	v_mov_b32_e32 v122, 0
	v_mov_b32_e32 v123, 0
	v_mov_b32_e32 v124, 0
	v_mov_b32_e32 v125, 0
	v_mov_b32_e32 v126, 0
	v_mov_b32_e32 v127, 0
	s_and_saveexec_b64 s[70:71], s[4:5]
	s_cbranch_execz .LBB0_1104
	s_barrier
.LBB0_1104:
	s_or_b64 exec, exec, s[70:71]
	v_readfirstlane_b32 s65, v144
	v_lshl_add_u64 v[6:7], v[0:1], 0, s[12:13]
	s_mov_b32 m0, s65
	v_readfirstlane_b32 s65, v145
	s_waitcnt vmcnt(4)
	s_barrier
	global_load_lds_dwordx4 v[6:7], off
	v_lshl_add_u64 v[0:1], v[0:1], 0, s[16:17]
	s_mov_b32 m0, s65
	v_readfirstlane_b32 s65, v146
	global_load_lds_dwordx4 v[0:1], off
	v_lshl_add_u64 v[0:1], v[2:3], 0, s[12:13]
	s_mov_b32 m0, s65
	v_readfirstlane_b32 s65, v147
	global_load_lds_dwordx4 v[0:1], off
	v_lshl_add_u64 v[0:1], v[2:3], 0, s[16:17]
	s_mov_b32 m0, s65
	v_readfirstlane_b32 s65, v148
	global_load_lds_dwordx4 v[0:1], off
	v_lshl_add_u64 v[0:1], v[4:5], 0, s[12:13]
	s_mov_b32 m0, s65
	v_readfirstlane_b32 s65, v149
	global_load_lds_dwordx4 v[0:1], off
	v_lshl_add_u64 v[0:1], v[4:5], 0, s[16:17]
	s_mov_b32 m0, s65
	s_add_u32 s66, s6, s66
	global_load_lds_dwordx4 v[0:1], off
	s_addc_u32 s67, s7, s67
	s_add_u32 s68, s6, s68
	v_mov_b32_e32 v0, 0
	s_addc_u32 s69, s7, s69
	s_mov_b32 s65, -2
	v_mov_b32_e32 v1, v0
	v_mov_b32_e32 v2, v0
	v_mov_b32_e32 v3, v0
	v_mov_b32_e32 v4, v0
	v_mov_b32_e32 v5, v0
	v_mov_b32_e32 v6, v0
	v_mov_b32_e32 v7, v0
	s_waitcnt vmcnt(6)
	s_barrier

; #define STAGE(P, BASE, br, kt) do { const char* _gb = (const char*)(BASE) + ((size_t)(br) * K + (size_t)(kt) * BK) * 2; \
;     __builtin_amdgcn_global_load_lds((const unsigned*)(_gb + loff0), (unsigned*)((char*)(P) + tid * 16), 16, 0, 0); \
;     __builtin_amdgcn_global_load_lds((const unsigned*)(_gb + (size_t)K * 128 + loff0), (unsigned*)((char*)(P) + tid * 16 + 8192), 16, 0, 0); } while (0)
; #define WAIT_V(n) asm volatile("s_waitcnt vmcnt(" #n ")" ::: "memory")
; #define BAR __builtin_amdgcn_s_barrier()
; template <int EPI> ...
;     ...
;   f32x4 acc[2][2][4][2] = {};
;   bf16x8 At[4][2], B0[2][2], B1[2][2];
;   int nt = K / BK;
;   const int aoff0 = lds_byte(wr * 64 + fr, fq * 8), aoff1 = lds_byte(wr * 64 + fr, 32 + fq * 8);
;   const int brw = wc * 32 + (fr >> 2) * 8 + (fr & 3);
;   const int boff0 = lds_byte(brw, fq * 8), boff1 = lds_byte(brw, 32 + fq * 8);
;   unsigned loff0;
;   { int _r, _c; stage_rc(tid * 16, _r, _c); loff0 = (unsigned)(_r * K + _c) * 2u; }
;   STAGE(SB(0, 0), Bt, bcol, 0); STAGE(SA(0, 0), A, brow, 0);
;   STAGE(SB(0, 1), Bt, bcol + HALF, 0); STAGE(SA(0, 1), A, brow + HALF, 0);
;   if (wr == 1) BAR;
;   WAIT_V(4); BAR;
;   STAGE(SB(1, 0), Bt, bcol, 1); STAGE(SA(1, 0), A, brow, 1); STAGE(SB(1, 1), Bt, bcol + HALF, 1);
;   WAIT_V(6); BAR;
.LBB0_1148:
	s_mov_b32 s60, s70
	s_add_i32 s70, s70, s33
	s_cmpk_lt_i32 s70, 0x401
	s_cselect_b64 s[58:59], -1, 0
	s_and_b64 s[58:59], s[44:45], s[58:59]
	s_and_b64 s[58:59], s[58:59], exec
	s_cselect_b32 s58, s86, s91
	s_add_i32 s60, s58, s60
	s_cmpk_gt_i32 s60, 0x3ff
	s_mov_b64 s[58:59], -1
	s_cbranch_scc1 .LBB0_1147
	s_sub_i32 s60, 0x3ff, s60
	s_ashr_i32 s58, s60, 31
	s_lshr_b32 s58, s58, 26
	s_add_i32 s58, s60, s58
	s_and_b32 s59, s58, 0xffc0
	s_sub_i32 s59, s60, s59
	s_bfe_i32 s60, s59, 0x80000
	s_bfe_u32 s60, s60, 0x3000c
	s_add_i32 s60, s59, s60
	s_bfe_i32 s61, s60, 0x80000
	s_and_b32 s60, s60, 0xf8
	s_sub_i32 s59, s59, s60
	s_sext_i32_i16 s61, s61
	s_sext_i32_i8 s59, s59
	s_lshl_b32 s58, s58, 5
	s_ashr_i32 s62, s61, 3
	s_and_b32 s58, s58, 0xfffff800
	s_lshl_b32 s71, s59, 8
	s_add_i32 s71, s71, s58
	s_lshl_b32 s58, s62, 8
	s_mul_i32 s64, s62, 0x2c0000
	s_mul_hi_i32 s65, s58, 0x2c00
	s_add_u32 s60, s66, s64
	s_addc_u32 s61, s67, s65
	v_readfirstlane_b32 s59, v135
	s_mul_i32 s75, s71, 0x2c00
	v_lshl_add_u64 v[0:1], s[60:61], 0, v[128:129]
	s_mov_b32 m0, s59
	v_readfirstlane_b32 s59, v136
	s_mul_hi_i32 s74, s71, 0x2c00
	s_add_u32 s60, s14, s75
	global_load_lds_dwordx4 v[0:1], off
	v_lshl_add_u64 v[2:3], v[0:1], 0, s[8:9]
	s_mov_b32 m0, s59
	s_addc_u32 s61, s43, s74
	global_load_lds_dwordx4 v[2:3], off
	v_lshl_add_u64 v[2:3], s[60:61], 0, v[128:129]
	s_mul_i32 s60, s62, 0x160000
	v_readfirstlane_b32 s59, v137
	s_ashr_i32 s61, s60, 31
	s_mov_b32 m0, s59
	v_readfirstlane_b32 s59, v138
	s_lshl_b64 s[60:61], s[60:61], 1
	global_load_lds_dwordx4 v[2:3], off
	s_mov_b32 m0, s59
	s_add_u32 s59, s66, s60
	s_addc_u32 s63, s67, s61
	s_add_u32 s62, s59, 0x160000
	v_lshl_add_u64 v[4:5], v[2:3], 0, s[8:9]
	s_addc_u32 s63, s63, 0
	v_readfirstlane_b32 s59, v139
	global_load_lds_dwordx4 v[4:5], off
	v_lshl_add_u64 v[4:5], s[62:63], 0, v[128:129]
	s_mov_b32 m0, s59
	v_readfirstlane_b32 s59, v140
	global_load_lds_dwordx4 v[4:5], off
	s_mov_b32 m0, s59
	s_or_b32 s59, s71, 0x80
	s_mul_i32 s73, s59, 0x2c00
	s_mul_hi_i32 s72, s59, 0x2c00
	s_add_u32 s62, s14, s73
	v_lshl_add_u64 v[6:7], v[4:5], 0, s[8:9]
	s_addc_u32 s63, s43, s72
	v_readfirstlane_b32 s59, v141
	global_load_lds_dwordx4 v[6:7], off
	v_lshl_add_u64 v[6:7], s[62:63], 0, v[128:129]
	s_mov_b32 m0, s59
	v_readfirstlane_b32 s59, v142
	global_load_lds_dwordx4 v[6:7], off
	v_lshl_add_u64 v[6:7], v[6:7], 0, s[8:9]
	s_mov_b32 m0, s59
	s_nop 0
	global_load_lds_dwordx4 v[6:7], off
	v_mov_b32_e32 v8, 0
	v_mov_b32_e32 v9, 0
	v_mov_b32_e32 v10, 0
	v_mov_b32_e32 v11, 0
	v_mov_b32_e32 v12, 0
	v_mov_b32_e32 v13, 0
	v_mov_b32_e32 v14, 0
	v_mov_b32_e32 v15, 0
	v_mov_b32_e32 v16, 0
	v_mov_b32_e32 v17, 0
	v_mov_b32_e32 v18, 0
	v_mov_b32_e32 v19, 0
	v_mov_b32_e32 v20, 0
	v_mov_b32_e32 v21, 0
	v_mov_b32_e32 v22, 0
	v_mov_b32_e32 v23, 0
	v_mov_b32_e32 v24, 0
	v_mov_b32_e32 v25, 0
	v_mov_b32_e32 v26, 0
	v_mov_b32_e32 v27, 0
	v_mov_b32_e32 v28, 0
	v_mov_b32_e32 v29, 0
	v_mov_b32_e32 v30, 0
	v_mov_b32_e32 v31, 0
	v_mov_b32_e32 v32, 0
	v_mov_b32_e32 v33, 0
	v_mov_b32_e32 v34, 0
	v_mov_b32_e32 v35, 0
	v_mov_b32_e32 v36, 0
	v_mov_b32_e32 v37, 0
	v_mov_b32_e32 v38, 0
	v_mov_b32_e32 v39, 0
	v_mov_b32_e32 v40, 0
	v_mov_b32_e32 v41, 0
	v_mov_b32_e32 v42, 0
	v_mov_b32_e32 v43, 0
	v_mov_b32_e32 v44, 0
	v_mov_b32_e32 v45, 0
	v_mov_b32_e32 v46, 0
	v_mov_b32_e32 v47, 0
	v_mov_b32_e32 v48, 0
	v_mov_b32_e32 v49, 0
	v_mov_b32_e32 v50, 0
	v_mov_b32_e32 v51, 0
	v_mov_b32_e32 v52, 0
	v_mov_b32_e32 v53, 0
	v_mov_b32_e32 v54, 0
	v_mov_b32_e32 v55, 0
	v_mov_b32_e32 v56, 0
	v_mov_b32_e32 v57, 0
	v_mov_b32_e32 v58, 0
	v_mov_b32_e32 v59, 0
	v_mov_b32_e32 v60, 0
	v_mov_b32_e32 v61, 0
	v_mov_b32_e32 v62, 0
	v_mov_b32_e32 v63, 0
	v_mov_b32_e32 v64, 0
	v_mov_b32_e32 v65, 0
	v_mov_b32_e32 v66, 0
	v_mov_b32_e32 v67, 0
	v_mov_b32_e32 v68, 0
	v_mov_b32_e32 v69, 0
	v_mov_b32_e32 v70, 0
	v_mov_b32_e32 v71, 0
	v_mov_b32_e32 v72, 0
	v_mov_b32_e32 v73, 0
	v_mov_b32_e32 v74, 0
	v_mov_b32_e32 v75, 0
	v_mov_b32_e32 v76, 0
	v_mov_b32_e32 v77, 0
	v_mov_b32_e32 v78, 0
	v_mov_b32_e32 v79, 0
	v_mov_b32_e32 v80, 0
	v_mov_b32_e32 v81, 0
	v_mov_b32_e32 v82, 0
	v_mov_b32_e32 v83, 0
	v_mov_b32_e32 v84, 0
	v_mov_b32_e32 v85, 0
	v_mov_b32_e32 v86, 0
	v_mov_b32_e32 v87, 0
	v_mov_b32_e32 v88, 0
	v_mov_b32_e32 v89, 0
	v_mov_b32_e32 v90, 0
	v_mov_b32_e32 v91, 0
	v_mov_b32_e32 v92, 0
	v_mov_b32_e32 v93, 0
	v_mov_b32_e32 v94, 0
	v_mov_b32_e32 v95, 0
	v_mov_b32_e32 v96, 0
	v_mov_b32_e32 v97, 0
	v_mov_b32_e32 v98, 0
	v_mov_b32_e32 v99, 0
	v_mov_b32_e32 v100, 0
	v_mov_b32_e32 v101, 0
	v_mov_b32_e32 v102, 0
	v_mov_b32_e32 v103, 0
	v_mov_b32_e32 v104, 0
	v_mov_b32_e32 v105, 0
	v_mov_b32_e32 v106, 0
	v_mov_b32_e32 v107, 0
	v_mov_b32_e32 v108, 0
	v_mov_b32_e32 v109, 0
	v_mov_b32_e32 v110, 0
	v_mov_b32_e32 v111, 0
	v_mov_b32_e32 v112, 0
	v_mov_b32_e32 v113, 0
	v_mov_b32_e32 v114, 0
	v_mov_b32_e32 v115, 0
	v_mov_b32_e32 v116, 0
	v_mov_b32_e32 v117, 0
	v_mov_b32_e32 v118, 0
	v_mov_b32_e32 v119, 0
	v_mov_b32_e32 v120, 0
	v_mov_b32_e32 v121, 0
	v_mov_b32_e32 v122, 0
	v_mov_b32_e32 v123, 0
	v_mov_b32_e32 v124, 0
	v_mov_b32_e32 v125, 0
	v_mov_b32_e32 v126, 0
	v_mov_b32_e32 v127, 0
	s_and_saveexec_b64 s[62:63], s[4:5]
	s_cbranch_execz .LBB0_1151
	s_barrier
.LBB0_1151:
	s_or_b64 exec, exec, s[62:63]
	v_readfirstlane_b32 s62, v143
	v_lshl_add_u64 v[6:7], v[0:1], 0, s[10:11]
	s_mov_b32 m0, s62
	v_readfirstlane_b32 s62, v144
	s_waitcnt vmcnt(4)
	s_barrier
	global_load_lds_dwordx4 v[6:7], off
	v_lshl_add_u64 v[0:1], v[0:1], 0, s[12:13]
	s_mov_b32 m0, s62
	v_readfirstlane_b32 s62, v145
	global_load_lds_dwordx4 v[0:1], off
	v_lshl_add_u64 v[0:1], v[2:3], 0, s[10:11]
	s_mov_b32 m0, s62
	v_readfirstlane_b32 s62, v146
	global_load_lds_dwordx4 v[0:1], off
	v_lshl_add_u64 v[0:1], v[2:3], 0, s[12:13]
	s_mov_b32 m0, s62
	v_readfirstlane_b32 s62, v147
	global_load_lds_dwordx4 v[0:1], off
	v_lshl_add_u64 v[0:1], v[4:5], 0, s[10:11]
	s_mov_b32 m0, s62
	v_readfirstlane_b32 s62, v148
	global_load_lds_dwordx4 v[0:1], off
	v_lshl_add_u64 v[0:1], v[4:5], 0, s[12:13]
	s_mov_b32 m0, s62
	s_ashr_i32 s59, s58, 31
	global_load_lds_dwordx4 v[0:1], off
	s_add_u32 s60, s6, s60
	s_addc_u32 s61, s7, s61
	s_add_u32 s62, s6, s75
	s_addc_u32 s63, s7, s74
	s_add_u32 s64, s6, s64
	v_mov_b32_e32 v0, 0
	s_addc_u32 s65, s7, s65
	s_mov_b32 s74, -2
	v_mov_b32_e32 v1, v0
	v_mov_b32_e32 v2, v0
	v_mov_b32_e32 v3, v0
	v_mov_b32_e32 v4, v0
	v_mov_b32_e32 v5, v0
	v_mov_b32_e32 v6, v0
	v_mov_b32_e32 v7, v0
	s_waitcnt vmcnt(6)
	s_barrier
